# GEMM1 K-loop: per-segment s_setprio flips deleted, one static s_setprio 1 for the younger wave-half (waves 4-7) before the loop, reset at phase end; on top of stage B
# speedup vs baseline: 1.0144x; 1.0144x over previous
; #define PG8_STAGE(bufoff, gbase, voff) do { _Pragma("unroll") for (int _i = 0; _i < 2; ++_i) \
;         __builtin_amdgcn_global_load_lds((const unsigned*)((const char*)(gbase) + (voff)[_i]), (LAS unsigned*)(lds + (bufoff) + ldsw + _i * 8192), 16, 0, 0); } while (0)
; #define PG8_WAIT_V(n) asm volatile("s_waitcnt vmcnt(" #n ")" ::: "memory")
; #define PG8_BAR __builtin_amdgcn_s_barrier()
; template <class Epi, class Sched, bool ALIGN_EPI = false, bool SP2 = true>
; DI void gemm_phase(LAS unsigned char* lds, const Gemm g, const Sched& S, const Epi& E, f32x4 (&acc)[2][2][4][2]) {
;     ...
;         if (wr == 1) PG8_BAR;
;         PG8_WAIT_V(2); PG8_BAR;
;         PG8_STAGE(PG8_SB(1, 0), cB + kstep, voffB); PG8_STAGE(PG8_SA(1, 0), cA + kstep, voffA); PG8_STAGE(PG8_SB(1, 1), cB + hstep + kstep, voffB);
;         PG8_WAIT_V(6); PG8_BAR;
.LBB0_140:
	s_cmp_lg_u32 s19, 1
	s_cbranch_scc1 .Lprio_done
	s_setprio 1

; #define PG8_STAGE(bufoff, gbase, voff) do { _Pragma("unroll") for (int _i = 0; _i < 2; ++_i) \
;         __builtin_amdgcn_global_load_lds((const unsigned*)((const char*)(gbase) + (voff)[_i]), (LAS unsigned*)(lds + (bufoff) + ldsw + _i * 8192), 16, 0, 0); } while (0)
; #define PG8_LDA(dst, b, h) do { _Pragma("unroll") for (int m = 0; m < 4; ++m) _Pragma("unroll") for (int k = 0; k < 2; ++k) dst[m][k] = *(const LAS bf16x8*)(lds + PG8_SA(b, h) + aoff + m * 2048 + k * 1024); } while (0)
; #define PG8_LDB(dst, b, h) do { _Pragma("unroll") for (int n = 0; n < 2; ++n) _Pragma("unroll") for (int k = 0; k < 2; ++k) dst[n][k] = *(const LAS bf16x8*)(lds + PG8_SB(b, h) + boff + n * 2048 + k * 1024); } while (0)
; #define PG8_MMA(ai, bj, At, Bt) do { __builtin_amdgcn_s_setprio(1); _Pragma("unroll") for (int m = 0; m < 4; ++m) _Pragma("unroll") for (int n = 0; n < 2; ++n) _Pragma("unroll") for (int k = 0; k < 2; ++k) \
;         acc[ai][bj][m][n] = __builtin_amdgcn_mfma_f32_16x16x32_bf16(Bt[n][k], At[m][k], acc[ai][bj][m][n], 0, 0, 0); __builtin_amdgcn_s_setprio(0); } while (0)
; #define PG8_WAIT_V(n) asm volatile("s_waitcnt vmcnt(" #n ")" ::: "memory")
; #define PG8_WAIT_L(n) asm volatile("s_waitcnt lgkmcnt(" #n ")" ::: "memory")
; #define PG8_BAR __builtin_amdgcn_s_barrier()
; #define PG8_SCHED __builtin_amdgcn_sched_barrier(0)
; template <class Epi, class Sched, bool ALIGN_EPI = false, bool SP2 = true>
; DI void gemm_phase(LAS unsigned char* lds, const Gemm g, const Sched& S, const Epi& E, f32x4 (&acc)[2][2][4][2]) {
;     ...
;             PG8_LDB(B0, 0, 0); PG8_LDB(B1, 0, 1); PG8_SCHED; PG8_LDA(At, 0, 0); PG8_STAGE(PG8_SA(1, 1), a1 + hstep, voffA);
;             PG8_WAIT_V(8); PG8_WAIT_L(0); PG8_BAR; PG8_MMA(0, 0, At, B0); PG8_MMA(0, 1, At, B1); PG8_BAR; PG8_SCHED;
;             PG8_LDA(At, 0, 1); PG8_STAGE(PG8_SB(0, 0), b2, voffB); PG8_STAGE(PG8_SB(0, 1), b2 + hstep, voffB); PG8_STAGE(PG8_SA(0, 0), a2, voffA);
;             PG8_WAIT_V(8); PG8_WAIT_L(0); PG8_BAR; PG8_MMA(1, 0, At, B0); PG8_MMA(1, 1, At, B1); PG8_BAR; PG8_SCHED;
.LBB0_159:
	ds_read_b128 v[150:153], v164
	ds_read_b128 v[154:157], v164 offset:1024
	ds_read_b128 v[158:161], v164 offset:2048
	ds_read_b128 v[168:171], v164 offset:3072
	ds_read_b128 v[172:175], v165
	ds_read_b128 v[180:183], v165 offset:1024
	ds_read_b128 v[184:187], v165 offset:2048
	ds_read_b128 v[188:191], v165 offset:3072
	s_add_u32 s30, s0, 0xfffc0080
	s_addc_u32 s31, s1, -1
	s_cmp_eq_u32 s62, 12
	s_cselect_b32 s35, s25, s31
	s_cselect_b32 s34, s52, s30
	s_cselect_b32 s31, s23, s55
	s_cselect_b32 s30, s53, s54
	v_lshl_add_u64 v[176:177], s[0:1], 0, v[146:147]
	s_add_i32 m0, s74, 0xc000
	ds_read_b128 v[192:195], v166
	ds_read_b128 v[196:199], v166 offset:1024
	ds_read_b128 v[202:205], v166 offset:2048
	ds_read_b128 v[206:209], v166 offset:3072
	ds_read_b128 v[210:213], v166 offset:4096
	ds_read_b128 v[214:217], v166 offset:5120
	ds_read_b128 v[218:221], v166 offset:6144
	ds_read_b128 v[222:225], v166 offset:7168
	global_load_lds_dwordx4 v[176:177], off
	v_lshl_add_u64 v[176:177], s[0:1], 0, v[148:149]
	s_add_i32 m0, s74, 0xe000
	s_nop 0
	global_load_lds_dwordx4 v[176:177], off
	s_waitcnt vmcnt(8)
	s_waitcnt lgkmcnt(0)
	s_barrier
	s_waitcnt lgkmcnt(0)
	v_mfma_f32_16x16x32_bf16 v[124:127], v[150:153], v[192:195], v[124:127]
	v_mfma_f32_16x16x32_bf16 v[120:123], v[158:161], v[192:195], v[120:123]
	v_mfma_f32_16x16x32_bf16 v[108:111], v[150:153], v[202:205], v[108:111]
	v_mfma_f32_16x16x32_bf16 v[104:107], v[158:161], v[202:205], v[104:107]
	v_mfma_f32_16x16x32_bf16 v[92:95], v[150:153], v[210:213], v[92:95]
	v_mfma_f32_16x16x32_bf16 v[88:91], v[158:161], v[210:213], v[88:91]
	v_mfma_f32_16x16x32_bf16 v[76:79], v[150:153], v[218:221], v[76:79]
	v_mfma_f32_16x16x32_bf16 v[72:75], v[158:161], v[218:221], v[72:75]
	v_mfma_f32_16x16x32_bf16 v[124:127], v[154:157], v[196:199], v[124:127]
	v_mfma_f32_16x16x32_bf16 v[120:123], v[168:171], v[196:199], v[120:123]
	v_mfma_f32_16x16x32_bf16 v[108:111], v[154:157], v[206:209], v[108:111]
	v_mfma_f32_16x16x32_bf16 v[104:107], v[168:171], v[206:209], v[104:107]
	v_mfma_f32_16x16x32_bf16 v[92:95], v[154:157], v[214:217], v[92:95]
	v_mfma_f32_16x16x32_bf16 v[88:91], v[168:171], v[214:217], v[88:91]
	v_mfma_f32_16x16x32_bf16 v[76:79], v[154:157], v[222:225], v[76:79]
	v_mfma_f32_16x16x32_bf16 v[72:75], v[168:171], v[222:225], v[72:75]
	v_mfma_f32_16x16x32_bf16 v[116:119], v[172:175], v[192:195], v[116:119]
	v_mfma_f32_16x16x32_bf16 v[112:115], v[184:187], v[192:195], v[112:115]
	v_mfma_f32_16x16x32_bf16 v[100:103], v[172:175], v[202:205], v[100:103]
	v_mfma_f32_16x16x32_bf16 v[96:99], v[184:187], v[202:205], v[96:99]
	v_mfma_f32_16x16x32_bf16 v[84:87], v[172:175], v[210:213], v[84:87]
	v_mfma_f32_16x16x32_bf16 v[80:83], v[184:187], v[210:213], v[80:83]
	v_mfma_f32_16x16x32_bf16 v[68:71], v[172:175], v[218:221], v[68:71]
	v_mfma_f32_16x16x32_bf16 v[64:67], v[184:187], v[218:221], v[64:67]
	v_mfma_f32_16x16x32_bf16 v[116:119], v[180:183], v[196:199], v[116:119]
	v_mfma_f32_16x16x32_bf16 v[112:115], v[188:191], v[196:199], v[112:115]
	v_mfma_f32_16x16x32_bf16 v[100:103], v[180:183], v[206:209], v[100:103]
	v_mfma_f32_16x16x32_bf16 v[96:99], v[188:191], v[206:209], v[96:99]
	v_mfma_f32_16x16x32_bf16 v[84:87], v[180:183], v[214:217], v[84:87]
	v_mfma_f32_16x16x32_bf16 v[80:83], v[188:191], v[214:217], v[80:83]
	v_mfma_f32_16x16x32_bf16 v[68:71], v[180:183], v[222:225], v[68:71]
	v_mfma_f32_16x16x32_bf16 v[64:67], v[188:191], v[222:225], v[64:67]
	s_barrier
	s_add_i32 s63, s82, s39
	v_lshl_add_u64 v[176:177], s[30:31], 0, v[130:131]
	s_mov_b32 m0, s63
	ds_read_b128 v[192:195], v166 offset:16384
	ds_read_b128 v[196:199], v166 offset:17408
	ds_read_b128 v[202:205], v166 offset:18432
	ds_read_b128 v[206:209], v166 offset:19456
	ds_read_b128 v[210:213], v166 offset:20480
	ds_read_b128 v[214:217], v166 offset:21504
	ds_read_b128 v[218:221], v166 offset:22528
	ds_read_b128 v[222:225], v166 offset:23552
	global_load_lds_dwordx4 v[176:177], off
	s_add_i32 m0, s63, 0x2000
	s_add_u32 s72, s30, 0x10000
	v_lshl_add_u64 v[226:227], s[30:31], 0, v[134:135]
	s_addc_u32 s73, s31, 0
	s_add_i32 s63, s83, s39
	global_load_lds_dwordx4 v[226:227], off
	v_lshl_add_u64 v[228:229], s[72:73], 0, v[130:131]
	s_mov_b32 m0, s63
	v_lshl_add_u64 v[230:231], s[34:35], 0, v[132:133]
	global_load_lds_dwordx4 v[228:229], off
	v_lshl_add_u64 v[228:229], s[72:73], 0, v[134:135]
	s_add_i32 m0, s63, 0x2000
	s_nop 0
	global_load_lds_dwordx4 v[228:229], off
	v_lshl_add_u64 v[228:229], s[34:35], 0, v[128:129]
	s_mov_b32 m0, s74
	s_nop 0
	global_load_lds_dwordx4 v[228:229], off
	s_mov_b32 m0, s75
	s_nop 0
	global_load_lds_dwordx4 v[230:231], off
	s_waitcnt vmcnt(8)
	s_waitcnt lgkmcnt(0)
	s_barrier
; #define PG8_STAGE(bufoff, gbase, voff) do { _Pragma("unroll") for (int _i = 0; _i < 2; ++_i) \
;         __builtin_amdgcn_global_load_lds((const unsigned*)((const char*)(gbase) + (voff)[_i]), (LAS unsigned*)(lds + (bufoff) + ldsw + _i * 8192), 16, 0, 0); } while (0)
; #define PG8_LDA(dst, b, h) do { _Pragma("unroll") for (int m = 0; m < 4; ++m) _Pragma("unroll") for (int k = 0; k < 2; ++k) dst[m][k] = *(const LAS bf16x8*)(lds + PG8_SA(b, h) + aoff + m * 2048 + k * 1024); } while (0)
; #define PG8_LDB(dst, b, h) do { _Pragma("unroll") for (int n = 0; n < 2; ++n) _Pragma("unroll") for (int k = 0; k < 2; ++k) dst[n][k] = *(const LAS bf16x8*)(lds + PG8_SB(b, h) + boff + n * 2048 + k * 1024); } while (0)
; #define PG8_MMA(ai, bj, At, Bt) do { __builtin_amdgcn_s_setprio(1); _Pragma("unroll") for (int m = 0; m < 4; ++m) _Pragma("unroll") for (int n = 0; n < 2; ++n) _Pragma("unroll") for (int k = 0; k < 2; ++k) \
;         acc[ai][bj][m][n] = __builtin_amdgcn_mfma_f32_16x16x32_bf16(Bt[n][k], At[m][k], acc[ai][bj][m][n], 0, 0, 0); __builtin_amdgcn_s_setprio(0); } while (0)
; #define PG8_WAIT_V(n) asm volatile("s_waitcnt vmcnt(" #n ")" ::: "memory")
; #define PG8_WAIT_L(n) asm volatile("s_waitcnt lgkmcnt(" #n ")" ::: "memory")
; #define PG8_BAR __builtin_amdgcn_s_barrier()
; #define PG8_SCHED __builtin_amdgcn_sched_barrier(0)
; template <class Epi, class Sched, bool ALIGN_EPI = false, bool SP2 = true>
; DI void gemm_phase(LAS unsigned char* lds, const Gemm g, const Sched& S, const Epi& E, f32x4 (&acc)[2][2][4][2]) {
;     ...
;             PG8_WAIT_V(8); PG8_WAIT_L(0); PG8_BAR; PG8_MMA(1, 0, At, B0); PG8_MMA(1, 1, At, B1); PG8_BAR; PG8_SCHED;
;             PG8_LDB(B0, 1, 0); PG8_LDB(B1, 1, 1); PG8_SCHED; PG8_LDA(At, 1, 0); PG8_STAGE(PG8_SA(0, 1), a2 + hstep, voffA);
;             PG8_WAIT_V(8); PG8_WAIT_L(0); PG8_BAR; PG8_MMA(0, 0, At, B0); PG8_MMA(0, 1, At, B1); PG8_BAR; PG8_SCHED;
	s_waitcnt lgkmcnt(0)
	v_mfma_f32_16x16x32_bf16 v[60:63], v[150:153], v[192:195], v[60:63]
	v_mfma_f32_16x16x32_bf16 v[56:59], v[158:161], v[192:195], v[56:59]
	v_mfma_f32_16x16x32_bf16 v[44:47], v[150:153], v[202:205], v[44:47]
	v_mfma_f32_16x16x32_bf16 v[40:43], v[158:161], v[202:205], v[40:43]
	v_mfma_f32_16x16x32_bf16 v[28:31], v[150:153], v[210:213], v[28:31]
	v_mfma_f32_16x16x32_bf16 v[24:27], v[158:161], v[210:213], v[24:27]
	v_mfma_f32_16x16x32_bf16 v[12:15], v[150:153], v[218:221], v[12:15]
	v_mfma_f32_16x16x32_bf16 v[8:11], v[158:161], v[218:221], v[8:11]
	v_mfma_f32_16x16x32_bf16 v[60:63], v[154:157], v[196:199], v[60:63]
	v_mfma_f32_16x16x32_bf16 v[56:59], v[168:171], v[196:199], v[56:59]
	v_mfma_f32_16x16x32_bf16 v[44:47], v[154:157], v[206:209], v[44:47]
	v_mfma_f32_16x16x32_bf16 v[40:43], v[168:171], v[206:209], v[40:43]
	v_mfma_f32_16x16x32_bf16 v[28:31], v[154:157], v[214:217], v[28:31]
	v_mfma_f32_16x16x32_bf16 v[24:27], v[168:171], v[214:217], v[24:27]
	v_mfma_f32_16x16x32_bf16 v[12:15], v[154:157], v[222:225], v[12:15]
	v_mfma_f32_16x16x32_bf16 v[8:11], v[168:171], v[222:225], v[8:11]
	v_mfma_f32_16x16x32_bf16 v[52:55], v[172:175], v[192:195], v[52:55]
	v_mfma_f32_16x16x32_bf16 v[48:51], v[184:187], v[192:195], v[48:51]
	v_mfma_f32_16x16x32_bf16 v[36:39], v[172:175], v[202:205], v[36:39]
	v_mfma_f32_16x16x32_bf16 v[32:35], v[184:187], v[202:205], v[32:35]
	v_mfma_f32_16x16x32_bf16 v[20:23], v[172:175], v[210:213], v[20:23]
	v_mfma_f32_16x16x32_bf16 v[16:19], v[184:187], v[210:213], v[16:19]
	v_mfma_f32_16x16x32_bf16 v[4:7], v[172:175], v[218:221], v[4:7]
	v_mfma_f32_16x16x32_bf16 v[0:3], v[184:187], v[218:221], v[0:3]
	v_mfma_f32_16x16x32_bf16 v[52:55], v[180:183], v[196:199], v[52:55]
	v_mfma_f32_16x16x32_bf16 v[48:51], v[188:191], v[196:199], v[48:51]
	v_mfma_f32_16x16x32_bf16 v[36:39], v[180:183], v[206:209], v[36:39]
	v_mfma_f32_16x16x32_bf16 v[32:35], v[188:191], v[206:209], v[32:35]
	v_mfma_f32_16x16x32_bf16 v[20:23], v[180:183], v[214:217], v[20:23]
	v_mfma_f32_16x16x32_bf16 v[16:19], v[188:191], v[214:217], v[16:19]
	v_mfma_f32_16x16x32_bf16 v[4:7], v[180:183], v[222:225], v[4:7]
	v_mfma_f32_16x16x32_bf16 v[0:3], v[188:191], v[222:225], v[0:3]
	s_barrier
	s_add_i32 s63, 0, 0x18000
	s_add_i32 s64, 0, 0x1c000
	v_add_u32_e32 v168, s63, v143
	v_add_u32_e32 v178, s64, v143
	ds_read_b128 v[150:153], v168
	ds_read_b128 v[154:157], v168 offset:1024
	ds_read_b128 v[158:161], v168 offset:2048
	ds_read_b128 v[168:171], v168 offset:3072
	ds_read_b128 v[172:175], v178
	ds_read_b128 v[180:183], v178 offset:1024
	ds_read_b128 v[184:187], v178 offset:2048
	ds_read_b128 v[188:191], v178 offset:3072
	s_add_u32 s34, s34, 0x40000
	s_addc_u32 s35, s35, 0
	s_mov_b32 m0, s76
	v_lshl_add_u64 v[232:233], s[34:35], 0, v[128:129]
	ds_read_b128 v[192:195], v166 offset:32768
	ds_read_b128 v[196:199], v166 offset:33792
	ds_read_b128 v[202:205], v166 offset:34816
	ds_read_b128 v[206:209], v166 offset:35840
	ds_read_b128 v[210:213], v166 offset:36864
	ds_read_b128 v[214:217], v166 offset:37888
	ds_read_b128 v[218:221], v166 offset:38912
	ds_read_b128 v[222:225], v166 offset:39936
	global_load_lds_dwordx4 v[232:233], off
	v_lshl_add_u64 v[232:233], s[34:35], 0, v[132:133]
	s_mov_b32 m0, s77
	s_nop 0
	global_load_lds_dwordx4 v[232:233], off
	s_waitcnt vmcnt(8)
	s_waitcnt lgkmcnt(0)
	s_barrier
	s_waitcnt lgkmcnt(0)
	v_mfma_f32_16x16x32_bf16 v[124:127], v[150:153], v[192:195], v[124:127]
	v_mfma_f32_16x16x32_bf16 v[120:123], v[158:161], v[192:195], v[120:123]
	v_mfma_f32_16x16x32_bf16 v[108:111], v[150:153], v[202:205], v[108:111]
	v_mfma_f32_16x16x32_bf16 v[104:107], v[158:161], v[202:205], v[104:107]
	v_mfma_f32_16x16x32_bf16 v[92:95], v[150:153], v[210:213], v[92:95]
	v_mfma_f32_16x16x32_bf16 v[88:91], v[158:161], v[210:213], v[88:91]
	v_mfma_f32_16x16x32_bf16 v[76:79], v[150:153], v[218:221], v[76:79]
	v_mfma_f32_16x16x32_bf16 v[72:75], v[158:161], v[218:221], v[72:75]
	v_mfma_f32_16x16x32_bf16 v[124:127], v[154:157], v[196:199], v[124:127]
	v_mfma_f32_16x16x32_bf16 v[120:123], v[168:171], v[196:199], v[120:123]
	v_mfma_f32_16x16x32_bf16 v[108:111], v[154:157], v[206:209], v[108:111]
	v_mfma_f32_16x16x32_bf16 v[104:107], v[168:171], v[206:209], v[104:107]
	v_mfma_f32_16x16x32_bf16 v[92:95], v[154:157], v[214:217], v[92:95]
	v_mfma_f32_16x16x32_bf16 v[88:91], v[168:171], v[214:217], v[88:91]
	v_mfma_f32_16x16x32_bf16 v[76:79], v[154:157], v[222:225], v[76:79]
	v_mfma_f32_16x16x32_bf16 v[72:75], v[168:171], v[222:225], v[72:75]
	v_mfma_f32_16x16x32_bf16 v[116:119], v[172:175], v[192:195], v[116:119]
	v_mfma_f32_16x16x32_bf16 v[112:115], v[184:187], v[192:195], v[112:115]
	v_mfma_f32_16x16x32_bf16 v[100:103], v[172:175], v[202:205], v[100:103]
	v_mfma_f32_16x16x32_bf16 v[96:99], v[184:187], v[202:205], v[96:99]
	v_mfma_f32_16x16x32_bf16 v[84:87], v[172:175], v[210:213], v[84:87]
	v_mfma_f32_16x16x32_bf16 v[80:83], v[184:187], v[210:213], v[80:83]
	v_mfma_f32_16x16x32_bf16 v[68:71], v[172:175], v[218:221], v[68:71]
	v_mfma_f32_16x16x32_bf16 v[64:67], v[184:187], v[218:221], v[64:67]
	v_mfma_f32_16x16x32_bf16 v[116:119], v[180:183], v[196:199], v[116:119]
	v_mfma_f32_16x16x32_bf16 v[112:115], v[188:191], v[196:199], v[112:115]
	v_mfma_f32_16x16x32_bf16 v[100:103], v[180:183], v[206:209], v[100:103]
	v_mfma_f32_16x16x32_bf16 v[96:99], v[188:191], v[206:209], v[96:99]
	v_mfma_f32_16x16x32_bf16 v[84:87], v[180:183], v[214:217], v[84:87]
	v_mfma_f32_16x16x32_bf16 v[80:83], v[188:191], v[214:217], v[80:83]
	v_mfma_f32_16x16x32_bf16 v[68:71], v[180:183], v[222:225], v[68:71]
	v_mfma_f32_16x16x32_bf16 v[64:67], v[188:191], v[222:225], v[64:67]
	s_barrier
; #define PG8_STAGE(bufoff, gbase, voff) do { _Pragma("unroll") for (int _i = 0; _i < 2; ++_i) \
;         __builtin_amdgcn_global_load_lds((const unsigned*)((const char*)(gbase) + (voff)[_i]), (LAS unsigned*)(lds + (bufoff) + ldsw + _i * 8192), 16, 0, 0); } while (0)
; #define PG8_LDA(dst, b, h) do { _Pragma("unroll") for (int m = 0; m < 4; ++m) _Pragma("unroll") for (int k = 0; k < 2; ++k) dst[m][k] = *(const LAS bf16x8*)(lds + PG8_SA(b, h) + aoff + m * 2048 + k * 1024); } while (0)
; #define PG8_MMA(ai, bj, At, Bt) do { __builtin_amdgcn_s_setprio(1); _Pragma("unroll") for (int m = 0; m < 4; ++m) _Pragma("unroll") for (int n = 0; n < 2; ++n) _Pragma("unroll") for (int k = 0; k < 2; ++k) \
;         acc[ai][bj][m][n] = __builtin_amdgcn_mfma_f32_16x16x32_bf16(Bt[n][k], At[m][k], acc[ai][bj][m][n], 0, 0, 0); __builtin_amdgcn_s_setprio(0); } while (0)
; #define PG8_WAIT_V(n) asm volatile("s_waitcnt vmcnt(" #n ")" ::: "memory")
; #define PG8_WAIT_L(n) asm volatile("s_waitcnt lgkmcnt(" #n ")" ::: "memory")
; #define PG8_BAR __builtin_amdgcn_s_barrier()
; #define PG8_SCHED __builtin_amdgcn_sched_barrier(0)
; template <class Epi, class Sched, bool ALIGN_EPI = false, bool SP2 = true>
; DI void gemm_phase(LAS unsigned char* lds, const Gemm g, const Sched& S, const Epi& E, f32x4 (&acc)[2][2][4][2]) {
;     ...
;             PG8_LDA(At, 1, 1); PG8_STAGE(PG8_SB(1, 0), b3, voffB); PG8_STAGE(PG8_SB(1, 1), b3 + hstep, voffB); PG8_STAGE(PG8_SA(1, 0), a3, voffA);
;             PG8_WAIT_V(8); PG8_WAIT_L(0); PG8_BAR; PG8_MMA(1, 0, At, B0); PG8_MMA(1, 1, At, B1); PG8_BAR; PG8_SCHED;
	s_add_i32 s34, s63, s39
	v_lshl_add_u64 v[176:177], v[176:177], 0, s[14:15]
	s_mov_b32 m0, s34
	ds_read_b128 v[192:195], v166 offset:49152
	ds_read_b128 v[196:199], v166 offset:50176
	ds_read_b128 v[202:205], v166 offset:51200
	ds_read_b128 v[206:209], v166 offset:52224
	ds_read_b128 v[210:213], v166 offset:53248
	ds_read_b128 v[214:217], v166 offset:54272
	ds_read_b128 v[218:221], v166 offset:55296
	ds_read_b128 v[222:225], v166 offset:56320
	global_load_lds_dwordx4 v[176:177], off
	s_add_i32 m0, s34, 0x2000
	s_add_u32 s30, s30, 0x10080
	v_lshl_add_u64 v[176:177], v[226:227], 0, s[14:15]
	s_addc_u32 s31, s31, 0
	s_add_i32 s34, s64, s39
	global_load_lds_dwordx4 v[176:177], off
	v_lshl_add_u64 v[176:177], s[30:31], 0, v[130:131]
	s_mov_b32 m0, s34
	s_nop 0
	global_load_lds_dwordx4 v[176:177], off
	v_lshl_add_u64 v[176:177], s[30:31], 0, v[134:135]
	s_add_i32 m0, s34, 0x2000
	s_nop 0
	global_load_lds_dwordx4 v[176:177], off
	v_lshl_add_u64 v[176:177], v[228:229], 0, s[14:15]
	s_mov_b32 m0, s80
	s_nop 0
	global_load_lds_dwordx4 v[176:177], off
	v_lshl_add_u64 v[176:177], v[230:231], 0, s[14:15]
	s_mov_b32 m0, s81
	s_nop 0
	global_load_lds_dwordx4 v[176:177], off
	s_waitcnt vmcnt(8)
	s_waitcnt lgkmcnt(0)
	s_barrier
	s_waitcnt lgkmcnt(0)
	v_mfma_f32_16x16x32_bf16 v[60:63], v[150:153], v[192:195], v[60:63]
	v_mfma_f32_16x16x32_bf16 v[56:59], v[158:161], v[192:195], v[56:59]
	v_mfma_f32_16x16x32_bf16 v[44:47], v[150:153], v[202:205], v[44:47]
	v_mfma_f32_16x16x32_bf16 v[40:43], v[158:161], v[202:205], v[40:43]
	v_mfma_f32_16x16x32_bf16 v[28:31], v[150:153], v[210:213], v[28:31]
	v_mfma_f32_16x16x32_bf16 v[24:27], v[158:161], v[210:213], v[24:27]
	v_mfma_f32_16x16x32_bf16 v[12:15], v[150:153], v[218:221], v[12:15]
	v_mfma_f32_16x16x32_bf16 v[8:11], v[158:161], v[218:221], v[8:11]
	v_mfma_f32_16x16x32_bf16 v[60:63], v[154:157], v[196:199], v[60:63]
	v_mfma_f32_16x16x32_bf16 v[56:59], v[168:171], v[196:199], v[56:59]
	v_mfma_f32_16x16x32_bf16 v[44:47], v[154:157], v[206:209], v[44:47]
	v_mfma_f32_16x16x32_bf16 v[40:43], v[168:171], v[206:209], v[40:43]
	v_mfma_f32_16x16x32_bf16 v[28:31], v[154:157], v[214:217], v[28:31]
	v_mfma_f32_16x16x32_bf16 v[24:27], v[168:171], v[214:217], v[24:27]
	v_mfma_f32_16x16x32_bf16 v[12:15], v[154:157], v[222:225], v[12:15]
	v_mfma_f32_16x16x32_bf16 v[8:11], v[168:171], v[222:225], v[8:11]
	v_mfma_f32_16x16x32_bf16 v[52:55], v[172:175], v[192:195], v[52:55]
	v_mfma_f32_16x16x32_bf16 v[48:51], v[184:187], v[192:195], v[48:51]
	v_mfma_f32_16x16x32_bf16 v[36:39], v[172:175], v[202:205], v[36:39]
	v_mfma_f32_16x16x32_bf16 v[32:35], v[184:187], v[202:205], v[32:35]
	v_mfma_f32_16x16x32_bf16 v[20:23], v[172:175], v[210:213], v[20:23]
	v_mfma_f32_16x16x32_bf16 v[16:19], v[184:187], v[210:213], v[16:19]
	v_mfma_f32_16x16x32_bf16 v[4:7], v[172:175], v[218:221], v[4:7]
	v_mfma_f32_16x16x32_bf16 v[0:3], v[184:187], v[218:221], v[0:3]
	v_mfma_f32_16x16x32_bf16 v[52:55], v[180:183], v[196:199], v[52:55]
	v_mfma_f32_16x16x32_bf16 v[48:51], v[188:191], v[196:199], v[48:51]
	v_mfma_f32_16x16x32_bf16 v[36:39], v[180:183], v[206:209], v[36:39]
	v_mfma_f32_16x16x32_bf16 v[32:35], v[188:191], v[206:209], v[32:35]
	v_mfma_f32_16x16x32_bf16 v[20:23], v[180:183], v[214:217], v[20:23]
	v_mfma_f32_16x16x32_bf16 v[16:19], v[188:191], v[214:217], v[16:19]
	v_mfma_f32_16x16x32_bf16 v[4:7], v[180:183], v[222:225], v[4:7]
	v_mfma_f32_16x16x32_bf16 v[0:3], v[188:191], v[222:225], v[0:3]
	s_barrier
	s_add_i32 s62, s62, 2
	s_add_u32 s0, s0, 0x100
	s_addc_u32 s1, s1, 0
	s_add_u32 s54, s54, 0x100
	s_addc_u32 s55, s55, 0
	s_cmp_gt_u32 s62, 13
	s_cbranch_scc0 .LBB0_159
	s_and_b64 vcc, exec, s[16:17]
	s_cbranch_vccz .LBB0_162
	s_barrier

; #define PG8_WAIT_V(n) asm volatile("s_waitcnt vmcnt(" #n ")" ::: "memory")
; #define PG8_BAR __builtin_amdgcn_s_barrier()
; template <class Epi, class Sched, bool ALIGN_EPI = false, bool SP2 = true>
; DI void gemm_phase(LAS unsigned char* lds, const Gemm g, const Sched& S, const Epi& E, f32x4 (&acc)[2][2][4][2]) {
;     ...
;     PG8_WAIT_V(0);
;     if constexpr (!ALIGN_EPI) { if (wr == 0) PG8_BAR; }
;     PG8_BAR;
.LBB0_341:
	s_setprio 0
	s_waitcnt vmcnt(0)
	s_barrier
